# hand-scheduled k-loop for the three 256x128 GEMM instances (phases 5,7,8): fragment reads pipelined, global prefetch issued 2 k-steps ahead
# speedup vs baseline: 1.0194x; 1.0194x over previous
.LBB0_59:
	s_and_b32 s2, s2, 7
	v_readlane_b32 s4, v251, 7
	s_or_b32 s11, s2, s4
	s_lshl_b32 s10, s16, 7
	s_mul_i32 s2, s11, 0x160000
	s_add_u32 s4, s18, s2
	v_readlane_b32 s72, v250, 53
	s_addc_u32 s5, s19, 0
	s_mul_i32 s2, s16, 0xb0000
	v_readlane_b32 s84, v249, 1
	v_mov_b32_e32 v56, v200
	s_add_u32 s6, s84, s2
	s_movk_i32 s2, 0xb00
	v_ashrrev_i32_e32 v57, 2, v56
	v_lshlrev_b32_e32 v0, 3, v56
	s_waitcnt vmcnt(0)
	v_and_b32_e32 v188, 24, v0
	v_mad_i64_i32 v[0:1], s[8:9], v57, s2, 0
	v_lshlrev_b64 v[178:179], 1, v[0:1]
	v_add_u32_e32 v0, 64, v57
	v_mad_i64_i32 v[0:1], s[8:9], v0, s2, 0
	s_mul_hi_u32 s7, s10, 0x1600
	v_readlane_b32 s85, v249, 2
	v_lshlrev_b64 v[180:181], 1, v[0:1]
	v_add_u32_e32 v0, 0x80, v57
	s_addc_u32 s7, s85, s7
	v_lshlrev_b32_e32 v196, 1, v188
	v_mad_i64_i32 v[44:45], s[8:9], v0, s2, 0
	v_add_u32_e32 v0, 0xc0, v57
	v_lshl_add_u64 v[176:177], s[4:5], 0, v[196:197]
	v_mad_i64_i32 v[48:49], s[8:9], v0, s2, 0
	v_lshl_add_u64 v[182:183], s[6:7], 0, v[196:197]
	v_lshl_add_u64 v[40:41], v[176:177], 0, v[178:179]
	v_lshl_add_u64 v[42:43], v[176:177], 0, v[180:181]
	v_lshl_add_u64 v[46:47], v[44:45], 1, v[176:177]
	v_lshl_add_u64 v[50:51], v[48:49], 1, v[176:177]
	v_lshl_add_u64 v[52:53], v[182:183], 0, v[178:179]
	v_lshl_add_u64 v[54:55], v[182:183], 0, v[180:181]
	global_load_dwordx4 v[16:19], v[40:41], off
	global_load_dwordx4 v[20:23], v[42:43], off
	global_load_dwordx4 v[24:27], v[46:47], off
	global_load_dwordx4 v[28:31], v[50:51], off
	global_load_dwordx4 v[32:35], v[52:53], off
	global_load_dwordx4 v[36:39], v[54:55], off
	global_load_dwordx4 v[128:131], v[40:41], off offset:64
	global_load_dwordx4 v[132:135], v[42:43], off offset:64
	global_load_dwordx4 v[136:139], v[46:47], off offset:64
	global_load_dwordx4 v[140:143], v[50:51], off offset:64
	global_load_dwordx4 v[144:147], v[52:53], off offset:64
	global_load_dwordx4 v[148:151], v[54:55], off offset:64
	v_and_b32_e32 v58, 0xfffff9f, v56
	v_lshrrev_b32_e32 v59, 1, v56
	v_and_b32_e32 v56, 0x5f, v56
	s_movk_i32 s2, 0x50
	v_and_b32_e32 v59, 16, v59
	v_mad_u32_u24 v56, v56, s2, 0
	v_mul_lo_u32 v57, v57, s2
	v_mul_lo_u32 v58, v58, s2
	v_add_u32_e32 v189, v56, v59
	v_add_u32_e32 v56, 0, v196
	v_mov_b32_e32 v0, 0
	v_add_u32_e32 v58, 0, v58
	v_add_u32_e32 v191, v56, v57
	s_mov_b32 s17, 64
	s_mov_b32 s18, 0
	v_mov_b32_e32 v1, v0
	v_mov_b32_e32 v2, v0
	v_mov_b32_e32 v3, v0
	v_mov_b32_e32 v4, v0
	v_mov_b32_e32 v5, v0
	v_mov_b32_e32 v6, v0
	v_mov_b32_e32 v7, v0
	v_mov_b32_e32 v8, v0
	v_mov_b32_e32 v9, v0
	v_mov_b32_e32 v10, v0
	v_mov_b32_e32 v11, v0
	v_mov_b32_e32 v12, v0
	v_mov_b32_e32 v13, v0
	v_mov_b32_e32 v14, v0
	v_mov_b32_e32 v15, v0
	v_lshlrev_b64 v[184:185], 1, v[44:45]
	v_lshlrev_b64 v[186:187], 1, v[48:49]
	v_add_u32_e32 v190, v58, v59
	v_mov_b32_e32 v40, v0
	v_mov_b32_e32 v41, v0
	v_mov_b32_e32 v42, v0
	v_mov_b32_e32 v43, v0
	v_mov_b32_e32 v44, v0
	v_mov_b32_e32 v45, v0
	v_mov_b32_e32 v46, v0
	v_mov_b32_e32 v47, v0
	s_waitcnt vmcnt(0)
	ds_write_b128 v191, v[16:19]
	ds_write_b128 v191, v[20:23] offset:5120
	ds_write_b128 v191, v[24:27] offset:10240
	ds_write_b128 v191, v[28:31] offset:15360
	ds_write_b128 v191, v[32:35] offset:20480
	ds_write_b128 v191, v[36:39] offset:25600
	v_mov_b32_e32 v16, v0
	v_mov_b32_e32 v17, v0
	v_mov_b32_e32 v18, v0
	v_mov_b32_e32 v19, v0
	v_mov_b32_e32 v20, v0
	v_mov_b32_e32 v21, v0
	v_mov_b32_e32 v22, v0
	v_mov_b32_e32 v23, v0
	v_mov_b32_e32 v24, v0
	v_mov_b32_e32 v25, v0
	v_mov_b32_e32 v26, v0
	v_mov_b32_e32 v27, v0
	v_mov_b32_e32 v28, v0
	v_mov_b32_e32 v29, v0
	v_mov_b32_e32 v30, v0
	v_mov_b32_e32 v31, v0
	v_mov_b32_e32 v32, v0
	v_mov_b32_e32 v33, v0
	v_mov_b32_e32 v34, v0
	v_mov_b32_e32 v35, v0
	v_mov_b32_e32 v36, v0
	v_mov_b32_e32 v37, v0
	v_mov_b32_e32 v38, v0
	v_mov_b32_e32 v39, v0
	v_mov_b32_e32 v48, v0
	v_mov_b32_e32 v49, v0
	v_mov_b32_e32 v50, v0
	v_mov_b32_e32 v51, v0
	v_mov_b32_e32 v52, v0
	v_mov_b32_e32 v53, v0
	v_mov_b32_e32 v54, v0
	v_mov_b32_e32 v55, v0
	v_mov_b32_e32 v56, v0
	v_mov_b32_e32 v57, v0
	v_mov_b32_e32 v58, v0
	v_mov_b32_e32 v59, v0
	v_mov_b32_e32 v60, v0
	v_mov_b32_e32 v61, v0
	v_mov_b32_e32 v62, v0
	v_mov_b32_e32 v63, v0
	v_mov_b32_e32 v64, v0
	v_mov_b32_e32 v65, v0
	v_mov_b32_e32 v66, v0
	v_mov_b32_e32 v67, v0
	v_mov_b32_e32 v68, v0
	v_mov_b32_e32 v69, v0
	v_mov_b32_e32 v70, v0
	v_mov_b32_e32 v71, v0
	v_mov_b32_e32 v72, v0
	v_mov_b32_e32 v73, v0
	v_mov_b32_e32 v74, v0
	v_mov_b32_e32 v75, v0
	v_mov_b32_e32 v76, v0
	v_mov_b32_e32 v77, v0
	v_mov_b32_e32 v78, v0
	v_mov_b32_e32 v79, v0
	v_mov_b32_e32 v80, v0
	v_mov_b32_e32 v81, v0
	v_mov_b32_e32 v82, v0
	v_mov_b32_e32 v83, v0
	v_mov_b32_e32 v84, v0
	v_mov_b32_e32 v85, v0
	v_mov_b32_e32 v86, v0
	v_mov_b32_e32 v87, v0
	v_mov_b32_e32 v88, v0
	v_mov_b32_e32 v89, v0
	v_mov_b32_e32 v90, v0
	v_mov_b32_e32 v91, v0
	v_mov_b32_e32 v92, v0
	v_mov_b32_e32 v93, v0
	v_mov_b32_e32 v94, v0
	v_mov_b32_e32 v95, v0
	v_mov_b32_e32 v96, v0
	v_mov_b32_e32 v97, v0
	v_mov_b32_e32 v98, v0
	v_mov_b32_e32 v99, v0
	v_mov_b32_e32 v100, v0
	v_mov_b32_e32 v101, v0
	v_mov_b32_e32 v102, v0
	v_mov_b32_e32 v103, v0
	v_mov_b32_e32 v104, v0
	v_mov_b32_e32 v105, v0
	v_mov_b32_e32 v106, v0
	v_mov_b32_e32 v107, v0
	v_mov_b32_e32 v108, v0
	v_mov_b32_e32 v109, v0
	v_mov_b32_e32 v110, v0
	v_mov_b32_e32 v111, v0
	v_mov_b32_e32 v112, v0
	v_mov_b32_e32 v113, v0
	v_mov_b32_e32 v114, v0
	v_mov_b32_e32 v115, v0
	v_mov_b32_e32 v116, v0
	v_mov_b32_e32 v117, v0
	v_mov_b32_e32 v118, v0
	v_mov_b32_e32 v119, v0
	v_mov_b32_e32 v120, v0
	v_mov_b32_e32 v121, v0
	v_mov_b32_e32 v122, v0
	v_mov_b32_e32 v123, v0
	v_mov_b32_e32 v124, v0
	v_mov_b32_e32 v125, v0
	v_mov_b32_e32 v126, v0
	v_mov_b32_e32 v127, v0
	v_readlane_b32 s73, v250, 54
	v_readlane_b32 s74, v250, 55
	v_readlane_b32 s75, v250, 56
	v_readlane_b32 s76, v250, 57
	v_readlane_b32 s77, v250, 58
	v_readlane_b32 s78, v250, 59
	v_readlane_b32 s79, v250, 60
	v_readlane_b32 s80, v250, 61
	v_readlane_b32 s81, v250, 62
	v_readlane_b32 s82, v250, 63
	v_readlane_b32 s83, v249, 0
	v_readlane_b32 s86, v249, 3
	v_readlane_b32 s87, v249, 4
	v_lshrrev_b32_e32 v242, 2, v200
	v_and_b32_e32 v243, 3, v200
	v_lshlrev_b32_e32 v243, 4, v243
	v_mul_u32_u24_e32 v242, 0x1600, v242
	v_add_u32_e32 v192, v242, v243
	v_add_u32_e32 v193, 0x58000, v192
	v_add_u32_e32 v194, 0xb0000, v192
	v_add_u32_e32 v201, 0x108000, v192
	s_waitcnt lgkmcnt(0)
	s_barrier
	s_branch .LBB0_61
.LBB0_61:
	ds_read_b128 v[202:205], v189 offset:20480
	ds_read_b128 v[184:187], v190
	ds_read_b128 v[208:211], v189 offset:23040
	ds_read_b128 v[234:237], v190 offset:2560
	ds_read_b128 v[238:241], v190 offset:5120
	s_add_u32 s44, s18, 2
	s_min_u32 s44, s44, 87
	s_lshl_b32 s44, s44, 6
	s_add_u32 s40, s4, s44
	s_addc_u32 s41, s5, 0
	s_add_u32 s42, s6, s44
	s_addc_u32 s43, s7, 0
	global_load_dwordx4 v[152:155], v192, s[40:41]
	global_load_dwordx4 v[156:159], v193, s[40:41]
	global_load_dwordx4 v[160:163], v194, s[40:41]
	global_load_dwordx4 v[164:167], v201, s[40:41]
	global_load_dwordx4 v[168:171], v192, s[42:43]
	global_load_dwordx4 v[172:175], v193, s[42:43]
	s_waitcnt lgkmcnt(3)
	v_mfma_f32_32x32x16_bf16 v[112:127], v[202:205], v[184:187], v[112:127]
	s_waitcnt lgkmcnt(2)
	v_mfma_f32_32x32x16_bf16 v[96:111], v[208:211], v[184:187], v[96:111]
	ds_read_b128 v[184:187], v190 offset:7680
	s_waitcnt lgkmcnt(2)
	v_mfma_f32_32x32x16_bf16 v[80:95], v[202:205], v[234:237], v[80:95]
	v_mfma_f32_32x32x16_bf16 v[64:79], v[208:211], v[234:237], v[64:79]
	ds_read_b128 v[176:179], v189 offset:20512
	ds_read_b128 v[234:237], v190 offset:32
	s_waitcnt lgkmcnt(3)
	v_mfma_f32_32x32x16_bf16 v[48:63], v[202:205], v[238:241], v[48:63]
	v_mfma_f32_32x32x16_bf16 v[32:47], v[208:211], v[238:241], v[32:47]
	ds_read_b128 v[180:183], v189 offset:23072
	ds_read_b128 v[238:241], v190 offset:2592
	s_waitcnt lgkmcnt(4)
	v_mfma_f32_32x32x16_bf16 v[16:31], v[202:205], v[184:187], v[16:31]
	v_mfma_f32_32x32x16_bf16 v[0:15], v[208:211], v[184:187], v[0:15]
	ds_read_b128 v[184:187], v190 offset:5152
	s_waitcnt lgkmcnt(3)
	v_mfma_f32_32x32x16_bf16 v[112:127], v[176:179], v[234:237], v[112:127]
	s_waitcnt lgkmcnt(2)
	v_mfma_f32_32x32x16_bf16 v[96:111], v[180:183], v[234:237], v[96:111]
	ds_read_b128 v[234:237], v190 offset:7712
	s_waitcnt vmcnt(6)
	s_waitcnt lgkmcnt(2)
	v_mfma_f32_32x32x16_bf16 v[80:95], v[176:179], v[238:241], v[80:95]
	ds_write_b128 v191, v[128:131] offset:30720
	v_mfma_f32_32x32x16_bf16 v[64:79], v[180:183], v[238:241], v[64:79]
	ds_write_b128 v191, v[132:135] offset:35840
	s_waitcnt lgkmcnt(3)
	v_mfma_f32_32x32x16_bf16 v[48:63], v[176:179], v[184:187], v[48:63]
	ds_write_b128 v191, v[136:139] offset:40960
	v_mfma_f32_32x32x16_bf16 v[32:47], v[180:183], v[184:187], v[32:47]
	ds_write_b128 v191, v[140:143] offset:46080
	s_waitcnt lgkmcnt(4)
	v_mfma_f32_32x32x16_bf16 v[16:31], v[176:179], v[234:237], v[16:31]
	ds_write_b128 v191, v[144:147] offset:51200
	v_mfma_f32_32x32x16_bf16 v[0:15], v[180:183], v[234:237], v[0:15]
	ds_write_b128 v191, v[148:151] offset:56320
	s_waitcnt lgkmcnt(0)
	s_barrier
	ds_read_b128 v[202:205], v189 offset:51200
	ds_read_b128 v[184:187], v190 offset:30720
	ds_read_b128 v[208:211], v189 offset:53760
	ds_read_b128 v[234:237], v190 offset:33280
	ds_read_b128 v[238:241], v190 offset:35840
	s_add_u32 s44, s18, 3
	s_min_u32 s44, s44, 87
	s_lshl_b32 s44, s44, 6
	s_add_u32 s40, s4, s44
	s_addc_u32 s41, s5, 0
	s_add_u32 s42, s6, s44
	s_addc_u32 s43, s7, 0
	global_load_dwordx4 v[128:131], v192, s[40:41]
	global_load_dwordx4 v[132:135], v193, s[40:41]
	global_load_dwordx4 v[136:139], v194, s[40:41]
	global_load_dwordx4 v[140:143], v201, s[40:41]
	global_load_dwordx4 v[144:147], v192, s[42:43]
	global_load_dwordx4 v[148:151], v193, s[42:43]
	s_waitcnt lgkmcnt(3)
	v_mfma_f32_32x32x16_bf16 v[112:127], v[202:205], v[184:187], v[112:127]
	s_waitcnt lgkmcnt(2)
	v_mfma_f32_32x32x16_bf16 v[96:111], v[208:211], v[184:187], v[96:111]
	ds_read_b128 v[184:187], v190 offset:38400
	s_waitcnt lgkmcnt(2)
	v_mfma_f32_32x32x16_bf16 v[80:95], v[202:205], v[234:237], v[80:95]
	v_mfma_f32_32x32x16_bf16 v[64:79], v[208:211], v[234:237], v[64:79]
	ds_read_b128 v[176:179], v189 offset:51232
	ds_read_b128 v[234:237], v190 offset:30752
	s_waitcnt lgkmcnt(3)
	v_mfma_f32_32x32x16_bf16 v[48:63], v[202:205], v[238:241], v[48:63]
	v_mfma_f32_32x32x16_bf16 v[32:47], v[208:211], v[238:241], v[32:47]
	ds_read_b128 v[180:183], v189 offset:53792
	ds_read_b128 v[238:241], v190 offset:33312
	s_waitcnt lgkmcnt(4)
	v_mfma_f32_32x32x16_bf16 v[16:31], v[202:205], v[184:187], v[16:31]
	v_mfma_f32_32x32x16_bf16 v[0:15], v[208:211], v[184:187], v[0:15]
	ds_read_b128 v[184:187], v190 offset:35872
	s_waitcnt lgkmcnt(3)
	v_mfma_f32_32x32x16_bf16 v[112:127], v[176:179], v[234:237], v[112:127]
	s_waitcnt lgkmcnt(2)
	v_mfma_f32_32x32x16_bf16 v[96:111], v[180:183], v[234:237], v[96:111]
	ds_read_b128 v[234:237], v190 offset:38432
	s_waitcnt vmcnt(6)
	s_waitcnt lgkmcnt(2)
	v_mfma_f32_32x32x16_bf16 v[80:95], v[176:179], v[238:241], v[80:95]
	ds_write_b128 v191, v[152:155]
	v_mfma_f32_32x32x16_bf16 v[64:79], v[180:183], v[238:241], v[64:79]
	ds_write_b128 v191, v[156:159] offset:5120
	s_waitcnt lgkmcnt(3)
	v_mfma_f32_32x32x16_bf16 v[48:63], v[176:179], v[184:187], v[48:63]
	ds_write_b128 v191, v[160:163] offset:10240
	v_mfma_f32_32x32x16_bf16 v[32:47], v[180:183], v[184:187], v[32:47]
	ds_write_b128 v191, v[164:167] offset:15360
	s_waitcnt lgkmcnt(4)
	v_mfma_f32_32x32x16_bf16 v[16:31], v[176:179], v[234:237], v[16:31]
	ds_write_b128 v191, v[168:171] offset:20480
	v_mfma_f32_32x32x16_bf16 v[0:15], v[180:183], v[234:237], v[0:15]
	ds_write_b128 v191, v[172:175] offset:25600
	s_add_u32 s18, s18, 2
	s_cmp_lt_u32 s18, 88
	s_waitcnt lgkmcnt(0)
	s_barrier
	s_cbranch_scc1 .LBB0_61
	s_branch .LBB0_63

.LBB0_75:
	s_and_b32 s4, s2, 7
	v_readlane_b32 s5, v251, 7
	s_or_b32 s11, s4, s5
	v_readlane_b32 s16, v250, 53
	s_lshr_b32 s10, s2, 3
	s_lshl_b32 s2, s11, 19
	v_readlane_b32 s22, v250, 59
	v_mov_b32_e32 v13, v200
	v_readlane_b32 s23, v250, 60
	s_add_u32 s4, s22, s2
	v_readlane_b32 s26, v250, 63
	v_ashrrev_i32_e32 v38, 2, v13
	v_lshlrev_b32_e32 v0, 3, v13
	s_addc_u32 s5, s23, 0
	s_lshl_b32 s2, s10, 18
	s_waitcnt vmcnt(0)
	v_and_b32_e32 v188, 24, v0
	v_add_u32_e32 v46, 0x80, v38
	v_readlane_b32 s27, v249, 0
	s_add_u32 s6, s26, s2
	v_lshlrev_b32_e32 v196, 1, v188
	v_add_u32_e32 v42, 64, v38
	v_ashrrev_i32_e32 v47, 31, v46
	v_add_u32_e32 v50, 0xc0, v38
	s_addc_u32 s7, s27, 0
	v_lshl_add_u64 v[176:177], s[4:5], 0, v[196:197]
	v_ashrrev_i32_e32 v39, 31, v38
	v_ashrrev_i32_e32 v43, 31, v42
	v_lshlrev_b64 v[4:5], 11, v[46:47]
	v_ashrrev_i32_e32 v51, 31, v50
	v_lshlrev_b64 v[0:1], 11, v[38:39]
	v_lshlrev_b64 v[2:3], 11, v[42:43]
	v_lshl_add_u64 v[48:49], v[176:177], 0, v[4:5]
	v_lshlrev_b64 v[4:5], 11, v[50:51]
	v_lshl_add_u64 v[178:179], s[6:7], 0, v[196:197]
	v_lshl_add_u64 v[40:41], v[176:177], 0, v[0:1]
	v_lshl_add_u64 v[44:45], v[176:177], 0, v[2:3]
	v_lshl_add_u64 v[52:53], v[176:177], 0, v[4:5]
	v_lshl_add_u64 v[54:55], v[178:179], 0, v[0:1]
	v_lshl_add_u64 v[56:57], v[178:179], 0, v[2:3]
	global_load_dwordx4 v[14:17], v[40:41], off
	global_load_dwordx4 v[18:21], v[44:45], off
	global_load_dwordx4 v[22:25], v[48:49], off
	global_load_dwordx4 v[26:29], v[52:53], off
	global_load_dwordx4 v[30:33], v[54:55], off
	global_load_dwordx4 v[34:37], v[56:57], off
	global_load_dwordx4 v[128:131], v[40:41], off offset:64
	global_load_dwordx4 v[132:135], v[44:45], off offset:64
	global_load_dwordx4 v[136:139], v[48:49], off offset:64
	global_load_dwordx4 v[140:143], v[52:53], off offset:64
	global_load_dwordx4 v[144:147], v[54:55], off offset:64
	global_load_dwordx4 v[148:151], v[56:57], off offset:64
	v_and_b32_e32 v58, 0xfffff9f, v13
	v_lshrrev_b32_e32 v59, 1, v13
	v_and_b32_e32 v13, 0x5f, v13
	s_movk_i32 s2, 0x50
	v_and_b32_e32 v59, 16, v59
	v_mad_u32_u24 v13, v13, s2, 0
	v_mul_lo_u32 v60, v38, s2
	v_mul_lo_u32 v58, v58, s2
	v_add_u32_e32 v189, v13, v59
	v_add_u32_e32 v13, 0, v196
	v_readlane_b32 s17, v250, 54
	v_mov_b32_e32 v0, 0
	v_lshlrev_b64 v[38:39], 10, v[38:39]
	v_add_u32_e32 v58, 0, v58
	v_lshlrev_b64 v[42:43], 10, v[42:43]
	v_lshlrev_b64 v[46:47], 10, v[46:47]
	v_lshlrev_b64 v[50:51], 10, v[50:51]
	v_add_u32_e32 v191, v13, v60
	s_mov_b32 s16, 64
	s_mov_b32 s17, 0
	v_mov_b32_e32 v1, v0
	v_mov_b32_e32 v2, v0
	v_mov_b32_e32 v3, v0
	v_mov_b32_e32 v4, v0
	v_mov_b32_e32 v5, v0
	v_mov_b32_e32 v6, v0
	v_mov_b32_e32 v7, v0
	v_mov_b32_e32 v8, v0
	v_mov_b32_e32 v9, v0
	v_mov_b32_e32 v10, v0
	v_mov_b32_e32 v11, v0
	v_mov_b32_e32 v12, v0
	v_lshlrev_b64 v[180:181], 1, v[38:39]
	v_add_u32_e32 v190, v58, v59
	v_lshlrev_b64 v[182:183], 1, v[42:43]
	v_lshlrev_b64 v[184:185], 1, v[46:47]
	v_lshlrev_b64 v[186:187], 1, v[50:51]
	v_mov_b32_e32 v13, v0
	v_mov_b32_e32 v38, v0
	v_mov_b32_e32 v39, v0
	s_waitcnt vmcnt(0)
	ds_write_b128 v191, v[14:17]
	ds_write_b128 v191, v[18:21] offset:5120
	ds_write_b128 v191, v[22:25] offset:10240
	ds_write_b128 v191, v[26:29] offset:15360
	ds_write_b128 v191, v[30:33] offset:20480
	ds_write_b128 v191, v[34:37] offset:25600
	v_mov_b32_e32 v14, v0
	v_mov_b32_e32 v15, v0
	v_mov_b32_e32 v16, v0
	v_mov_b32_e32 v17, v0
	v_mov_b32_e32 v18, v0
	v_mov_b32_e32 v19, v0
	v_mov_b32_e32 v20, v0
	v_mov_b32_e32 v21, v0
	v_mov_b32_e32 v22, v0
	v_mov_b32_e32 v23, v0
	v_mov_b32_e32 v24, v0
	v_mov_b32_e32 v25, v0
	v_mov_b32_e32 v26, v0
	v_mov_b32_e32 v27, v0
	v_mov_b32_e32 v28, v0
	v_mov_b32_e32 v29, v0
	v_mov_b32_e32 v30, v0
	v_mov_b32_e32 v31, v0
	v_mov_b32_e32 v32, v0
	v_mov_b32_e32 v33, v0
	v_mov_b32_e32 v34, v0
	v_mov_b32_e32 v35, v0
	v_mov_b32_e32 v36, v0
	v_mov_b32_e32 v37, v0
	v_mov_b32_e32 v40, v0
	v_mov_b32_e32 v41, v0
	v_mov_b32_e32 v42, v0
	v_mov_b32_e32 v43, v0
	v_mov_b32_e32 v44, v0
	v_mov_b32_e32 v45, v0
	v_mov_b32_e32 v46, v0
	v_mov_b32_e32 v47, v0
	v_mov_b32_e32 v48, v0
	v_mov_b32_e32 v49, v0
	v_mov_b32_e32 v50, v0
	v_mov_b32_e32 v51, v0
	v_mov_b32_e32 v52, v0
	v_mov_b32_e32 v53, v0
	v_mov_b32_e32 v54, v0
	v_mov_b32_e32 v55, v0
	v_mov_b32_e32 v56, v0
	v_mov_b32_e32 v57, v0
	v_mov_b32_e32 v58, v0
	v_mov_b32_e32 v59, v0
	v_mov_b32_e32 v60, v0
	v_mov_b32_e32 v61, v0
	v_mov_b32_e32 v62, v0
	v_mov_b32_e32 v63, v0
	v_mov_b32_e32 v64, v0
	v_mov_b32_e32 v65, v0
	v_mov_b32_e32 v66, v0
	v_mov_b32_e32 v67, v0
	v_mov_b32_e32 v68, v0
	v_mov_b32_e32 v69, v0
	v_mov_b32_e32 v70, v0
	v_mov_b32_e32 v71, v0
	v_mov_b32_e32 v72, v0
	v_mov_b32_e32 v73, v0
	v_mov_b32_e32 v74, v0
	v_mov_b32_e32 v75, v0
	v_mov_b32_e32 v76, v0
	v_mov_b32_e32 v77, v0
	v_mov_b32_e32 v78, v0
	v_mov_b32_e32 v79, v0
	v_mov_b32_e32 v80, v0
	v_mov_b32_e32 v81, v0
	v_mov_b32_e32 v82, v0
	v_mov_b32_e32 v83, v0
	v_mov_b32_e32 v84, v0
	v_mov_b32_e32 v85, v0
	v_mov_b32_e32 v86, v0
	v_mov_b32_e32 v87, v0
	v_mov_b32_e32 v88, v0
	v_mov_b32_e32 v89, v0
	v_mov_b32_e32 v90, v0
	v_mov_b32_e32 v91, v0
	v_mov_b32_e32 v92, v0
	v_mov_b32_e32 v93, v0
	v_mov_b32_e32 v94, v0
	v_mov_b32_e32 v95, v0
	v_mov_b32_e32 v96, v0
	v_mov_b32_e32 v97, v0
	v_mov_b32_e32 v98, v0
	v_mov_b32_e32 v99, v0
	v_mov_b32_e32 v100, v0
	v_mov_b32_e32 v101, v0
	v_mov_b32_e32 v102, v0
	v_mov_b32_e32 v103, v0
	v_mov_b32_e32 v104, v0
	v_mov_b32_e32 v105, v0
	v_mov_b32_e32 v106, v0
	v_mov_b32_e32 v107, v0
	v_mov_b32_e32 v108, v0
	v_mov_b32_e32 v109, v0
	v_mov_b32_e32 v110, v0
	v_mov_b32_e32 v111, v0
	v_mov_b32_e32 v112, v0
	v_mov_b32_e32 v113, v0
	v_mov_b32_e32 v114, v0
	v_mov_b32_e32 v115, v0
	v_mov_b32_e32 v116, v0
	v_mov_b32_e32 v117, v0
	v_mov_b32_e32 v118, v0
	v_mov_b32_e32 v119, v0
	v_mov_b32_e32 v120, v0
	v_mov_b32_e32 v121, v0
	v_mov_b32_e32 v122, v0
	v_mov_b32_e32 v123, v0
	v_mov_b32_e32 v124, v0
	v_mov_b32_e32 v125, v0
	v_mov_b32_e32 v126, v0
	v_mov_b32_e32 v127, v0
	v_readlane_b32 s18, v250, 55
	v_readlane_b32 s19, v250, 56
	v_readlane_b32 s20, v250, 57
	v_readlane_b32 s21, v250, 58
	v_readlane_b32 s24, v250, 61
	v_readlane_b32 s25, v250, 62
	v_readlane_b32 s28, v249, 1
	v_readlane_b32 s29, v249, 2
	v_readlane_b32 s30, v249, 3
	v_readlane_b32 s31, v249, 4
	v_lshrrev_b32_e32 v242, 2, v200
	v_and_b32_e32 v243, 3, v200
	v_lshlrev_b32_e32 v243, 4, v243
	v_lshl_add_u32 v192, v242, 11, v243
	v_add_u32_e32 v193, 0x20000, v192
	v_add_u32_e32 v194, 0x40000, v192
	v_add_u32_e32 v201, 0x60000, v192
	s_waitcnt lgkmcnt(0)
	s_barrier
	s_branch .LBB0_77
.LBB0_77:
	ds_read_b128 v[202:205], v189 offset:20480
	ds_read_b128 v[184:187], v190
	ds_read_b128 v[208:211], v189 offset:23040
	ds_read_b128 v[234:237], v190 offset:2560
	ds_read_b128 v[238:241], v190 offset:5120
	s_add_u32 s44, s17, 2
	s_min_u32 s44, s44, 31
	s_lshl_b32 s44, s44, 6
	s_add_u32 s40, s4, s44
	s_addc_u32 s41, s5, 0
	s_add_u32 s42, s6, s44
	s_addc_u32 s43, s7, 0
	global_load_dwordx4 v[152:155], v192, s[40:41]
	global_load_dwordx4 v[156:159], v193, s[40:41]
	global_load_dwordx4 v[160:163], v194, s[40:41]
	global_load_dwordx4 v[164:167], v201, s[40:41]
	global_load_dwordx4 v[168:171], v192, s[42:43]
	global_load_dwordx4 v[172:175], v193, s[42:43]
	s_waitcnt lgkmcnt(3)
	v_mfma_f32_32x32x16_bf16 v[112:127], v[202:205], v[184:187], v[112:127]
	s_waitcnt lgkmcnt(2)
	v_mfma_f32_32x32x16_bf16 v[96:111], v[208:211], v[184:187], v[96:111]
	ds_read_b128 v[184:187], v190 offset:7680
	s_waitcnt lgkmcnt(2)
	v_mfma_f32_32x32x16_bf16 v[80:95], v[202:205], v[234:237], v[80:95]
	v_mfma_f32_32x32x16_bf16 v[64:79], v[208:211], v[234:237], v[64:79]
	ds_read_b128 v[176:179], v189 offset:20512
	ds_read_b128 v[234:237], v190 offset:32
	s_waitcnt lgkmcnt(3)
	v_mfma_f32_32x32x16_bf16 v[48:63], v[202:205], v[238:241], v[48:63]
	v_mfma_f32_32x32x16_bf16 v[32:47], v[208:211], v[238:241], v[32:47]
	ds_read_b128 v[180:183], v189 offset:23072
	ds_read_b128 v[238:241], v190 offset:2592
	s_waitcnt lgkmcnt(4)
	v_mfma_f32_32x32x16_bf16 v[16:31], v[202:205], v[184:187], v[16:31]
	v_mfma_f32_32x32x16_bf16 v[0:15], v[208:211], v[184:187], v[0:15]
	ds_read_b128 v[184:187], v190 offset:5152
	s_waitcnt lgkmcnt(3)
	v_mfma_f32_32x32x16_bf16 v[112:127], v[176:179], v[234:237], v[112:127]
	s_waitcnt lgkmcnt(2)
	v_mfma_f32_32x32x16_bf16 v[96:111], v[180:183], v[234:237], v[96:111]
	ds_read_b128 v[234:237], v190 offset:7712
	s_waitcnt vmcnt(6)
	s_waitcnt lgkmcnt(2)
	v_mfma_f32_32x32x16_bf16 v[80:95], v[176:179], v[238:241], v[80:95]
	ds_write_b128 v191, v[128:131] offset:30720
	v_mfma_f32_32x32x16_bf16 v[64:79], v[180:183], v[238:241], v[64:79]
	ds_write_b128 v191, v[132:135] offset:35840
	s_waitcnt lgkmcnt(3)
	v_mfma_f32_32x32x16_bf16 v[48:63], v[176:179], v[184:187], v[48:63]
	ds_write_b128 v191, v[136:139] offset:40960
	v_mfma_f32_32x32x16_bf16 v[32:47], v[180:183], v[184:187], v[32:47]
	ds_write_b128 v191, v[140:143] offset:46080
	s_waitcnt lgkmcnt(4)
	v_mfma_f32_32x32x16_bf16 v[16:31], v[176:179], v[234:237], v[16:31]
	ds_write_b128 v191, v[144:147] offset:51200
	v_mfma_f32_32x32x16_bf16 v[0:15], v[180:183], v[234:237], v[0:15]
	ds_write_b128 v191, v[148:151] offset:56320
	s_waitcnt lgkmcnt(0)
	s_barrier
	ds_read_b128 v[202:205], v189 offset:51200
	ds_read_b128 v[184:187], v190 offset:30720
	ds_read_b128 v[208:211], v189 offset:53760
	ds_read_b128 v[234:237], v190 offset:33280
	ds_read_b128 v[238:241], v190 offset:35840
	s_add_u32 s44, s17, 3
	s_min_u32 s44, s44, 31
	s_lshl_b32 s44, s44, 6
	s_add_u32 s40, s4, s44
	s_addc_u32 s41, s5, 0
	s_add_u32 s42, s6, s44
	s_addc_u32 s43, s7, 0
	global_load_dwordx4 v[128:131], v192, s[40:41]
	global_load_dwordx4 v[132:135], v193, s[40:41]
	global_load_dwordx4 v[136:139], v194, s[40:41]
	global_load_dwordx4 v[140:143], v201, s[40:41]
	global_load_dwordx4 v[144:147], v192, s[42:43]
	global_load_dwordx4 v[148:151], v193, s[42:43]
	s_waitcnt lgkmcnt(3)
	v_mfma_f32_32x32x16_bf16 v[112:127], v[202:205], v[184:187], v[112:127]
	s_waitcnt lgkmcnt(2)
	v_mfma_f32_32x32x16_bf16 v[96:111], v[208:211], v[184:187], v[96:111]
	ds_read_b128 v[184:187], v190 offset:38400
	s_waitcnt lgkmcnt(2)
	v_mfma_f32_32x32x16_bf16 v[80:95], v[202:205], v[234:237], v[80:95]
	v_mfma_f32_32x32x16_bf16 v[64:79], v[208:211], v[234:237], v[64:79]
	ds_read_b128 v[176:179], v189 offset:51232
	ds_read_b128 v[234:237], v190 offset:30752
	s_waitcnt lgkmcnt(3)
	v_mfma_f32_32x32x16_bf16 v[48:63], v[202:205], v[238:241], v[48:63]
	v_mfma_f32_32x32x16_bf16 v[32:47], v[208:211], v[238:241], v[32:47]
	ds_read_b128 v[180:183], v189 offset:53792
	ds_read_b128 v[238:241], v190 offset:33312
	s_waitcnt lgkmcnt(4)
	v_mfma_f32_32x32x16_bf16 v[16:31], v[202:205], v[184:187], v[16:31]
	v_mfma_f32_32x32x16_bf16 v[0:15], v[208:211], v[184:187], v[0:15]
	ds_read_b128 v[184:187], v190 offset:35872
	s_waitcnt lgkmcnt(3)
	v_mfma_f32_32x32x16_bf16 v[112:127], v[176:179], v[234:237], v[112:127]
	s_waitcnt lgkmcnt(2)
	v_mfma_f32_32x32x16_bf16 v[96:111], v[180:183], v[234:237], v[96:111]
	ds_read_b128 v[234:237], v190 offset:38432
	s_waitcnt vmcnt(6)
	s_waitcnt lgkmcnt(2)
	v_mfma_f32_32x32x16_bf16 v[80:95], v[176:179], v[238:241], v[80:95]
	ds_write_b128 v191, v[152:155]
	v_mfma_f32_32x32x16_bf16 v[64:79], v[180:183], v[238:241], v[64:79]
	ds_write_b128 v191, v[156:159] offset:5120
	s_waitcnt lgkmcnt(3)
	v_mfma_f32_32x32x16_bf16 v[48:63], v[176:179], v[184:187], v[48:63]
	ds_write_b128 v191, v[160:163] offset:10240
	v_mfma_f32_32x32x16_bf16 v[32:47], v[180:183], v[184:187], v[32:47]
	ds_write_b128 v191, v[164:167] offset:15360
	s_waitcnt lgkmcnt(4)
	v_mfma_f32_32x32x16_bf16 v[16:31], v[176:179], v[234:237], v[16:31]
	ds_write_b128 v191, v[168:171] offset:20480
	v_mfma_f32_32x32x16_bf16 v[0:15], v[180:183], v[234:237], v[0:15]
	ds_write_b128 v191, v[172:175] offset:25600
	s_add_u32 s17, s17, 2
	s_cmp_lt_u32 s17, 32
	s_waitcnt lgkmcnt(0)
	s_barrier
	s_cbranch_scc1 .LBB0_77
	s_branch .LBB0_74

.LBB0_106:
	s_and_b32 s2, s2, 7
	v_readlane_b32 s4, v251, 7
	s_or_b32 s16, s2, s4
	s_lshl_b32 s4, s15, 7
	s_lshl_b32 s14, s16, 19
	v_mov_b32_e32 v56, v200
	s_add_u32 s6, s20, s14
	s_mov_b32 s5, s3
	s_addc_u32 s7, s21, 0
	v_ashrrev_i32_e32 v36, 2, v56
	v_lshlrev_b32_e32 v0, 3, v56
	s_lshl_b64 s[8:9], s[4:5], 11
	v_readlane_b32 s10, v249, 19
	s_waitcnt vmcnt(0)
	v_and_b32_e32 v188, 24, v0
	v_add_u32_e32 v44, 0x80, v36
	v_readlane_b32 s11, v249, 20
	s_add_u32 s8, s10, s8
	v_lshlrev_b32_e32 v196, 1, v188
	v_add_u32_e32 v40, 64, v36
	v_ashrrev_i32_e32 v45, 31, v44
	v_add_u32_e32 v48, 0xc0, v36
	s_addc_u32 s9, s11, s9
	v_lshl_add_u64 v[176:177], s[6:7], 0, v[196:197]
	v_ashrrev_i32_e32 v37, 31, v36
	v_ashrrev_i32_e32 v41, 31, v40
	v_lshlrev_b64 v[4:5], 11, v[44:45]
	v_ashrrev_i32_e32 v49, 31, v48
	v_lshlrev_b64 v[0:1], 11, v[36:37]
	v_lshlrev_b64 v[2:3], 11, v[40:41]
	v_lshl_add_u64 v[46:47], v[176:177], 0, v[4:5]
	v_lshlrev_b64 v[4:5], 11, v[48:49]
	v_lshl_add_u64 v[178:179], s[8:9], 0, v[196:197]
	v_lshl_add_u64 v[38:39], v[176:177], 0, v[0:1]
	v_lshl_add_u64 v[42:43], v[176:177], 0, v[2:3]
	v_lshl_add_u64 v[50:51], v[176:177], 0, v[4:5]
	v_lshl_add_u64 v[52:53], v[178:179], 0, v[0:1]
	v_lshl_add_u64 v[54:55], v[178:179], 0, v[2:3]
	global_load_dwordx4 v[12:15], v[38:39], off
	global_load_dwordx4 v[16:19], v[42:43], off
	global_load_dwordx4 v[20:23], v[46:47], off
	global_load_dwordx4 v[24:27], v[50:51], off
	global_load_dwordx4 v[28:31], v[52:53], off
	global_load_dwordx4 v[32:35], v[54:55], off
	global_load_dwordx4 v[128:131], v[38:39], off offset:64
	global_load_dwordx4 v[132:135], v[42:43], off offset:64
	global_load_dwordx4 v[136:139], v[46:47], off offset:64
	global_load_dwordx4 v[140:143], v[50:51], off offset:64
	global_load_dwordx4 v[144:147], v[52:53], off offset:64
	global_load_dwordx4 v[148:151], v[54:55], off offset:64
	v_and_b32_e32 v57, 0xfffff9f, v56
	v_lshrrev_b32_e32 v58, 1, v56
	v_and_b32_e32 v56, 0x5f, v56
	s_movk_i32 s2, 0x50
	v_and_b32_e32 v58, 16, v58
	v_mad_u32_u24 v56, v56, s2, 0
	v_mul_lo_u32 v59, v36, s2
	v_mul_lo_u32 v57, v57, s2
	v_add_u32_e32 v189, v56, v58
	v_add_u32_e32 v56, 0, v196
	v_mov_b32_e32 v0, 0
	v_lshlrev_b64 v[36:37], 10, v[36:37]
	v_add_u32_e32 v57, 0, v57
	v_lshlrev_b64 v[40:41], 10, v[40:41]
	v_lshlrev_b64 v[44:45], 10, v[44:45]
	v_lshlrev_b64 v[48:49], 10, v[48:49]
	v_add_u32_e32 v191, v56, v59
	s_mov_b32 s5, 64
	s_mov_b32 s17, 0
	v_mov_b32_e32 v1, v0
	v_mov_b32_e32 v2, v0
	v_mov_b32_e32 v3, v0
	v_mov_b32_e32 v4, v0
	v_mov_b32_e32 v5, v0
	v_mov_b32_e32 v6, v0
	v_mov_b32_e32 v7, v0
	v_mov_b32_e32 v8, v0
	v_mov_b32_e32 v9, v0
	v_mov_b32_e32 v10, v0
	v_mov_b32_e32 v11, v0
	v_lshlrev_b64 v[180:181], 1, v[36:37]
	v_add_u32_e32 v190, v57, v58
	v_lshlrev_b64 v[182:183], 1, v[40:41]
	v_lshlrev_b64 v[184:185], 1, v[44:45]
	v_lshlrev_b64 v[186:187], 1, v[48:49]
	v_mov_b32_e32 v36, v0
	v_mov_b32_e32 v37, v0
	v_mov_b32_e32 v38, v0
	v_mov_b32_e32 v39, v0
	v_mov_b32_e32 v40, v0
	v_mov_b32_e32 v41, v0
	v_mov_b32_e32 v42, v0
	s_waitcnt vmcnt(0)
	ds_write_b128 v191, v[12:15]
	ds_write_b128 v191, v[16:19] offset:5120
	ds_write_b128 v191, v[20:23] offset:10240
	ds_write_b128 v191, v[24:27] offset:15360
	ds_write_b128 v191, v[28:31] offset:20480
	ds_write_b128 v191, v[32:35] offset:25600
	v_mov_b32_e32 v12, v0
	v_mov_b32_e32 v13, v0
	v_mov_b32_e32 v14, v0
	v_mov_b32_e32 v15, v0
	v_mov_b32_e32 v16, v0
	v_mov_b32_e32 v17, v0
	v_mov_b32_e32 v18, v0
	v_mov_b32_e32 v19, v0
	v_mov_b32_e32 v20, v0
	v_mov_b32_e32 v21, v0
	v_mov_b32_e32 v22, v0
	v_mov_b32_e32 v23, v0
	v_mov_b32_e32 v24, v0
	v_mov_b32_e32 v25, v0
	v_mov_b32_e32 v26, v0
	v_mov_b32_e32 v27, v0
	v_mov_b32_e32 v28, v0
	v_mov_b32_e32 v29, v0
	v_mov_b32_e32 v30, v0
	v_mov_b32_e32 v31, v0
	v_mov_b32_e32 v32, v0
	v_mov_b32_e32 v33, v0
	v_mov_b32_e32 v34, v0
	v_mov_b32_e32 v35, v0
	v_mov_b32_e32 v43, v0
	v_mov_b32_e32 v44, v0
	v_mov_b32_e32 v45, v0
	v_mov_b32_e32 v46, v0
	v_mov_b32_e32 v47, v0
	v_mov_b32_e32 v48, v0
	v_mov_b32_e32 v49, v0
	v_mov_b32_e32 v50, v0
	v_mov_b32_e32 v51, v0
	v_mov_b32_e32 v52, v0
	v_mov_b32_e32 v53, v0
	v_mov_b32_e32 v54, v0
	v_mov_b32_e32 v55, v0
	v_mov_b32_e32 v56, v0
	v_mov_b32_e32 v57, v0
	v_mov_b32_e32 v58, v0
	v_mov_b32_e32 v59, v0
	v_mov_b32_e32 v60, v0
	v_mov_b32_e32 v61, v0
	v_mov_b32_e32 v62, v0
	v_mov_b32_e32 v63, v0
	v_mov_b32_e32 v64, v0
	v_mov_b32_e32 v65, v0
	v_mov_b32_e32 v66, v0
	v_mov_b32_e32 v67, v0
	v_mov_b32_e32 v68, v0
	v_mov_b32_e32 v69, v0
	v_mov_b32_e32 v70, v0
	v_mov_b32_e32 v71, v0
	v_mov_b32_e32 v72, v0
	v_mov_b32_e32 v73, v0
	v_mov_b32_e32 v74, v0
	v_mov_b32_e32 v75, v0
	v_mov_b32_e32 v76, v0
	v_mov_b32_e32 v77, v0
	v_mov_b32_e32 v78, v0
	v_mov_b32_e32 v79, v0
	v_mov_b32_e32 v80, v0
	v_mov_b32_e32 v81, v0
	v_mov_b32_e32 v82, v0
	v_mov_b32_e32 v83, v0
	v_mov_b32_e32 v84, v0
	v_mov_b32_e32 v85, v0
	v_mov_b32_e32 v86, v0
	v_mov_b32_e32 v87, v0
	v_mov_b32_e32 v88, v0
	v_mov_b32_e32 v89, v0
	v_mov_b32_e32 v90, v0
	v_mov_b32_e32 v91, v0
	v_mov_b32_e32 v92, v0
	v_mov_b32_e32 v93, v0
	v_mov_b32_e32 v94, v0
	v_mov_b32_e32 v95, v0
	v_mov_b32_e32 v96, v0
	v_mov_b32_e32 v97, v0
	v_mov_b32_e32 v98, v0
	v_mov_b32_e32 v99, v0
	v_mov_b32_e32 v100, v0
	v_mov_b32_e32 v101, v0
	v_mov_b32_e32 v102, v0
	v_mov_b32_e32 v103, v0
	v_mov_b32_e32 v104, v0
	v_mov_b32_e32 v105, v0
	v_mov_b32_e32 v106, v0
	v_mov_b32_e32 v107, v0
	v_mov_b32_e32 v108, v0
	v_mov_b32_e32 v109, v0
	v_mov_b32_e32 v110, v0
	v_mov_b32_e32 v111, v0
	v_mov_b32_e32 v112, v0
	v_mov_b32_e32 v113, v0
	v_mov_b32_e32 v114, v0
	v_mov_b32_e32 v115, v0
	v_mov_b32_e32 v116, v0
	v_mov_b32_e32 v117, v0
	v_mov_b32_e32 v118, v0
	v_mov_b32_e32 v119, v0
	v_mov_b32_e32 v120, v0
	v_mov_b32_e32 v121, v0
	v_mov_b32_e32 v122, v0
	v_mov_b32_e32 v123, v0
	v_mov_b32_e32 v124, v0
	v_mov_b32_e32 v125, v0
	v_mov_b32_e32 v126, v0
	v_mov_b32_e32 v127, v0
	v_lshrrev_b32_e32 v242, 2, v200
	v_and_b32_e32 v243, 3, v200
	v_lshlrev_b32_e32 v243, 4, v243
	v_lshl_add_u32 v192, v242, 11, v243
	v_add_u32_e32 v193, 0x20000, v192
	v_add_u32_e32 v194, 0x40000, v192
	v_add_u32_e32 v201, 0x60000, v192
	s_waitcnt lgkmcnt(0)
	s_barrier
	s_branch .LBB0_108
.LBB0_108:
	ds_read_b128 v[202:205], v189 offset:20480
	ds_read_b128 v[184:187], v190
	ds_read_b128 v[208:211], v189 offset:23040
	ds_read_b128 v[234:237], v190 offset:2560
	ds_read_b128 v[238:241], v190 offset:5120
	s_add_u32 s44, s17, 2
	s_min_u32 s44, s44, 31
	s_lshl_b32 s44, s44, 6
	s_add_u32 s40, s6, s44
	s_addc_u32 s41, s7, 0
	s_add_u32 s42, s8, s44
	s_addc_u32 s43, s9, 0
	global_load_dwordx4 v[152:155], v192, s[40:41]
	global_load_dwordx4 v[156:159], v193, s[40:41]
	global_load_dwordx4 v[160:163], v194, s[40:41]
	global_load_dwordx4 v[164:167], v201, s[40:41]
	global_load_dwordx4 v[168:171], v192, s[42:43]
	global_load_dwordx4 v[172:175], v193, s[42:43]
	s_waitcnt lgkmcnt(3)
	v_mfma_f32_32x32x16_bf16 v[112:127], v[202:205], v[184:187], v[112:127]
	s_waitcnt lgkmcnt(2)
	v_mfma_f32_32x32x16_bf16 v[96:111], v[208:211], v[184:187], v[96:111]
	ds_read_b128 v[184:187], v190 offset:7680
	s_waitcnt lgkmcnt(2)
	v_mfma_f32_32x32x16_bf16 v[80:95], v[202:205], v[234:237], v[80:95]
	v_mfma_f32_32x32x16_bf16 v[64:79], v[208:211], v[234:237], v[64:79]
	ds_read_b128 v[176:179], v189 offset:20512
	ds_read_b128 v[234:237], v190 offset:32
	s_waitcnt lgkmcnt(3)
	v_mfma_f32_32x32x16_bf16 v[48:63], v[202:205], v[238:241], v[48:63]
	v_mfma_f32_32x32x16_bf16 v[32:47], v[208:211], v[238:241], v[32:47]
	ds_read_b128 v[180:183], v189 offset:23072
	ds_read_b128 v[238:241], v190 offset:2592
	s_waitcnt lgkmcnt(4)
	v_mfma_f32_32x32x16_bf16 v[16:31], v[202:205], v[184:187], v[16:31]
	v_mfma_f32_32x32x16_bf16 v[0:15], v[208:211], v[184:187], v[0:15]
	ds_read_b128 v[184:187], v190 offset:5152
	s_waitcnt lgkmcnt(3)
	v_mfma_f32_32x32x16_bf16 v[112:127], v[176:179], v[234:237], v[112:127]
	s_waitcnt lgkmcnt(2)
	v_mfma_f32_32x32x16_bf16 v[96:111], v[180:183], v[234:237], v[96:111]
	ds_read_b128 v[234:237], v190 offset:7712
	s_waitcnt vmcnt(6)
	s_waitcnt lgkmcnt(2)
	v_mfma_f32_32x32x16_bf16 v[80:95], v[176:179], v[238:241], v[80:95]
	ds_write_b128 v191, v[128:131] offset:30720
	v_mfma_f32_32x32x16_bf16 v[64:79], v[180:183], v[238:241], v[64:79]
	ds_write_b128 v191, v[132:135] offset:35840
	s_waitcnt lgkmcnt(3)
	v_mfma_f32_32x32x16_bf16 v[48:63], v[176:179], v[184:187], v[48:63]
	ds_write_b128 v191, v[136:139] offset:40960
	v_mfma_f32_32x32x16_bf16 v[32:47], v[180:183], v[184:187], v[32:47]
	ds_write_b128 v191, v[140:143] offset:46080
	s_waitcnt lgkmcnt(4)
	v_mfma_f32_32x32x16_bf16 v[16:31], v[176:179], v[234:237], v[16:31]
	ds_write_b128 v191, v[144:147] offset:51200
	v_mfma_f32_32x32x16_bf16 v[0:15], v[180:183], v[234:237], v[0:15]
	ds_write_b128 v191, v[148:151] offset:56320
	s_waitcnt lgkmcnt(0)
	s_barrier
	ds_read_b128 v[202:205], v189 offset:51200
	ds_read_b128 v[184:187], v190 offset:30720
	ds_read_b128 v[208:211], v189 offset:53760
	ds_read_b128 v[234:237], v190 offset:33280
	ds_read_b128 v[238:241], v190 offset:35840
	s_add_u32 s44, s17, 3
	s_min_u32 s44, s44, 31
	s_lshl_b32 s44, s44, 6
	s_add_u32 s40, s6, s44
	s_addc_u32 s41, s7, 0
	s_add_u32 s42, s8, s44
	s_addc_u32 s43, s9, 0
	global_load_dwordx4 v[128:131], v192, s[40:41]
	global_load_dwordx4 v[132:135], v193, s[40:41]
	global_load_dwordx4 v[136:139], v194, s[40:41]
	global_load_dwordx4 v[140:143], v201, s[40:41]
	global_load_dwordx4 v[144:147], v192, s[42:43]
	global_load_dwordx4 v[148:151], v193, s[42:43]
	s_waitcnt lgkmcnt(3)
	v_mfma_f32_32x32x16_bf16 v[112:127], v[202:205], v[184:187], v[112:127]
	s_waitcnt lgkmcnt(2)
	v_mfma_f32_32x32x16_bf16 v[96:111], v[208:211], v[184:187], v[96:111]
	ds_read_b128 v[184:187], v190 offset:38400
	s_waitcnt lgkmcnt(2)
	v_mfma_f32_32x32x16_bf16 v[80:95], v[202:205], v[234:237], v[80:95]
	v_mfma_f32_32x32x16_bf16 v[64:79], v[208:211], v[234:237], v[64:79]
	ds_read_b128 v[176:179], v189 offset:51232
	ds_read_b128 v[234:237], v190 offset:30752
	s_waitcnt lgkmcnt(3)
	v_mfma_f32_32x32x16_bf16 v[48:63], v[202:205], v[238:241], v[48:63]
	v_mfma_f32_32x32x16_bf16 v[32:47], v[208:211], v[238:241], v[32:47]
	ds_read_b128 v[180:183], v189 offset:53792
	ds_read_b128 v[238:241], v190 offset:33312
	s_waitcnt lgkmcnt(4)
	v_mfma_f32_32x32x16_bf16 v[16:31], v[202:205], v[184:187], v[16:31]
	v_mfma_f32_32x32x16_bf16 v[0:15], v[208:211], v[184:187], v[0:15]
	ds_read_b128 v[184:187], v190 offset:35872
	s_waitcnt lgkmcnt(3)
	v_mfma_f32_32x32x16_bf16 v[112:127], v[176:179], v[234:237], v[112:127]
	s_waitcnt lgkmcnt(2)
	v_mfma_f32_32x32x16_bf16 v[96:111], v[180:183], v[234:237], v[96:111]
	ds_read_b128 v[234:237], v190 offset:38432
	s_waitcnt vmcnt(6)
	s_waitcnt lgkmcnt(2)
	v_mfma_f32_32x32x16_bf16 v[80:95], v[176:179], v[238:241], v[80:95]
	ds_write_b128 v191, v[152:155]
	v_mfma_f32_32x32x16_bf16 v[64:79], v[180:183], v[238:241], v[64:79]
	ds_write_b128 v191, v[156:159] offset:5120
	s_waitcnt lgkmcnt(3)
	v_mfma_f32_32x32x16_bf16 v[48:63], v[176:179], v[184:187], v[48:63]
	ds_write_b128 v191, v[160:163] offset:10240
	v_mfma_f32_32x32x16_bf16 v[32:47], v[180:183], v[184:187], v[32:47]
	ds_write_b128 v191, v[164:167] offset:15360
	s_waitcnt lgkmcnt(4)
	v_mfma_f32_32x32x16_bf16 v[16:31], v[176:179], v[234:237], v[16:31]
	ds_write_b128 v191, v[168:171] offset:20480
	v_mfma_f32_32x32x16_bf16 v[0:15], v[180:183], v[234:237], v[0:15]
	ds_write_b128 v191, v[172:175] offset:25600
	s_add_u32 s17, s17, 2
	s_cmp_lt_u32 s17, 32
	s_waitcnt lgkmcnt(0)
	s_barrier
	s_cbranch_scc1 .LBB0_108
	s_branch .LBB0_110
